# adds: hand-scheduled SwiGLU epilogue of the gate/up GEMM (same arithmetic; batched exp/rcp, packed +1, row scales read up front, 32-bit store offsets on scalar base; ~25% fewer VALU issue slots)
# speedup vs baseline: 1.0001x; 1.0001x over previous
; #define LAS __attribute__((address_space(3)))
; __device__ __forceinline__ unsigned cvtpk(float lo, float hi) { f32x2_t v = {lo, hi}; bf16x2_t b = __builtin_convertvector(v, bf16x2_t); return __builtin_bit_cast(unsigned, b); }
; __device__ __forceinline__ float silu2(float g2, float u2) { return (g2 * u2) * __builtin_amdgcn_rcpf(1.0f + __builtin_amdgcn_exp2f(g2)); }
; __device__ __forceinline__ void prenorm_commit(const PreNorm& p, LAS float* scr, int tid) {
;     if (tid < 256) { scr[tid] = rsqrtf(((p.st[0] + p.st[1]) + (p.st[2] + p.st[3])) * (1.0f / DM) + EPS); scr[256 + tid] = p.sw; }
;     asm volatile("s_waitcnt lgkmcnt(0)" ::: "memory"); __builtin_amdgcn_s_barrier(); asm volatile("" ::: "memory");
; }
;     __device__ __forceinline__ void operator()(const f32x4 (&acc)[2][2][4][2], const Unit& u, int wr, int wc, int fr, int fq, int tid, const Pre& pre) const {
;         prenorm_commit(pre, scr, tid);
;         const int row0 = u.pm * BM + wr * 64 + fr; const int col0 = u.pn * HALF + wc * 32 + 8 * fq;
;         const LAS float* sp = scr + 256 + wc * 32 + 8 * fq;
;         const f32x4 sg0 = *(const LAS f32x4*)sp * (-LOG2E), sg1 = *(const LAS f32x4*)(sp + 4) * (-LOG2E), su0 = *(const LAS f32x4*)(sp + HALF) * (-1.0f / LOG2E), su1 = *(const LAS f32x4*)(sp + HALF + 4) * (-1.0f / LOG2E);
; #pragma unroll
;         for (int ai = 0; ai < 2; ++ai)
; #pragma unroll
;             for (int m = 0; m < 4; ++m) { bf16_t* rowp = O + (size_t)(row0 + ai * HALF + m * 16) * FF + col0;
;                 const float rs = scr[ai * HALF + wr * 64 + m * 16 + fr]; const float rsg = rs * (-LOG2E), rsu = rs * (-1.0f / LOG2E);
;                 const f32x4 g0 = acc[ai][0][m][0] * rsg + sg0, g1 = acc[ai][0][m][1] * rsg + sg1, u0 = acc[ai][1][m][0] * rsu + su0, u1 = acc[ai][1][m][1] * rsu + su1;
;                 u32x4 w; w.x = cvtpk(silu2(g0[0], u0[0]), silu2(g0[1], u0[1])); w.y = cvtpk(silu2(g0[2], u0[2]), silu2(g0[3], u0[3]));
;                 w.z = cvtpk(silu2(g1[0], u1[0]), silu2(g1[1], u1[1])); w.w = cvtpk(silu2(g1[2], u1[2]), silu2(g1[3], u1[3]));
;                 *(u32x4*)rowp = w; }
.LBB0_173:
	s_or_b64 exec, exec, s[64:65]
	s_waitcnt lgkmcnt(0)
	s_barrier
	s_nop 0
	ds_read_b128 v[112:115], v167
	ds_read_b128 v[148:151], v167 offset:16
	ds_read_b128 v[154:157], v167 offset:528
	ds_read2_b32 v[230:231], v168 offset1:16
	ds_read2_b32 v[232:233], v168 offset0:32 offset1:48
	ds_read_b32 v234, v169
	ds_read2_b32 v[236:237], v168 offset0:144 offset1:160
	ds_read_b32 v238, v168 offset:704
	v_lshl_or_b32 v158, s53, 7, v170
	v_lshl_add_u32 v172, s52, 8, v165
	v_mul_u32_u24_e32 v239, 0x1600, v172
	v_lshl_add_u32 v239, v158, 1, v239
	s_waitcnt lgkmcnt(5)
	v_pk_mul_f32 v[146:147], v[112:113], s[44:45] op_sel_hi:[1,0]
	v_pk_mul_f32 v[144:145], v[114:115], s[44:45] op_sel_hi:[1,0]
	v_pk_mul_f32 v[112:113], v[150:151], s[44:45] op_sel_hi:[1,0]
	v_pk_mul_f32 v[114:115], v[148:149], s[44:45] op_sel_hi:[1,0]
	ds_read_b128 v[150:153], v167 offset:512
	v_pk_mul_f32 v[154:155], v[154:155], s[36:37] op_sel_hi:[1,0]
	s_waitcnt lgkmcnt(0)
	v_pk_mul_f32 v[148:149], v[152:153], s[36:37] op_sel_hi:[1,0]
	v_pk_mul_f32 v[150:151], v[150:151], s[36:37] op_sel_hi:[1,0]
	v_pk_mul_f32 v[152:153], v[156:157], s[36:37] op_sel_hi:[1,0]
	s_mov_b32 s100, 1.0
	s_mov_b32 s101, 1.0
	v_mul_f32_e32 v184, 0xbfb8aa3b, v230
	v_mul_f32_e32 v186, 0xbf317218, v230
	v_pk_fma_f32 v[128:129], v[128:129], v[184:185], v[146:147] op_sel_hi:[1,0,1] neg_lo:[0,0,1] neg_hi:[0,0,1]
	v_pk_fma_f32 v[130:131], v[130:131], v[184:185], v[144:145] op_sel_hi:[1,0,1] neg_lo:[0,0,1] neg_hi:[0,0,1]
	v_pk_fma_f32 v[124:125], v[124:125], v[184:185], v[114:115] op_sel_hi:[1,0,1] neg_lo:[0,0,1] neg_hi:[0,0,1]
	v_pk_fma_f32 v[126:127], v[126:127], v[184:185], v[112:113] op_sel_hi:[1,0,1] neg_lo:[0,0,1] neg_hi:[0,0,1]
	v_pk_fma_f32 v[120:121], v[120:121], v[186:187], v[150:151] op_sel_hi:[1,0,1] neg_lo:[0,0,1] neg_hi:[0,0,1]
	v_pk_fma_f32 v[122:123], v[122:123], v[186:187], v[148:149] op_sel_hi:[1,0,1] neg_lo:[0,0,1] neg_hi:[0,0,1]
	v_pk_fma_f32 v[116:117], v[116:117], v[186:187], v[154:155] op_sel_hi:[1,0,1] neg_lo:[0,0,1] neg_hi:[0,0,1]
	v_pk_fma_f32 v[118:119], v[118:119], v[186:187], v[152:153] op_sel_hi:[1,0,1] neg_lo:[0,0,1] neg_hi:[0,0,1]
	v_exp_f32_e32 v176, v128
	v_exp_f32_e32 v177, v129
	v_exp_f32_e32 v178, v130
	v_exp_f32_e32 v179, v131
	v_exp_f32_e32 v180, v124
	v_exp_f32_e32 v181, v125
	v_exp_f32_e32 v182, v126
	v_exp_f32_e32 v183, v127
	v_pk_mul_f32 v[120:121], v[128:129], v[120:121]
	v_pk_mul_f32 v[122:123], v[130:131], v[122:123]
	v_pk_mul_f32 v[116:117], v[124:125], v[116:117]
	v_pk_mul_f32 v[118:119], v[126:127], v[118:119]
	v_pk_add_f32 v[176:177], v[176:177], s[100:101]
	v_pk_add_f32 v[178:179], v[178:179], s[100:101]
	v_pk_add_f32 v[180:181], v[180:181], s[100:101]
	v_pk_add_f32 v[182:183], v[182:183], s[100:101]
	v_rcp_f32_e32 v176, v176
	v_rcp_f32_e32 v177, v177
	v_rcp_f32_e32 v178, v178
	v_rcp_f32_e32 v179, v179
	v_rcp_f32_e32 v180, v180
	v_rcp_f32_e32 v181, v181
	v_rcp_f32_e32 v182, v182
	v_rcp_f32_e32 v183, v183
	v_mov_b32_e32 v240, v239
	v_pk_mul_f32 v[120:121], v[120:121], v[176:177]
	v_pk_mul_f32 v[122:123], v[122:123], v[178:179]
	v_pk_mul_f32 v[116:117], v[116:117], v[180:181]
	v_pk_mul_f32 v[118:119], v[118:119], v[182:183]
	v_cvt_pk_bf16_f32 v188, v120, v121
	v_cvt_pk_bf16_f32 v189, v122, v123
	v_cvt_pk_bf16_f32 v190, v116, v117
	v_cvt_pk_bf16_f32 v191, v118, v119
	global_store_dwordx4 v240, v[188:191], s[16:17]
	v_mul_f32_e32 v184, 0xbfb8aa3b, v231
	v_mul_f32_e32 v186, 0xbf317218, v231
	v_pk_fma_f32 v[108:109], v[108:109], v[184:185], v[146:147] op_sel_hi:[1,0,1] neg_lo:[0,0,1] neg_hi:[0,0,1]
	v_pk_fma_f32 v[110:111], v[110:111], v[184:185], v[144:145] op_sel_hi:[1,0,1] neg_lo:[0,0,1] neg_hi:[0,0,1]
	v_pk_fma_f32 v[104:105], v[104:105], v[184:185], v[114:115] op_sel_hi:[1,0,1] neg_lo:[0,0,1] neg_hi:[0,0,1]
	v_pk_fma_f32 v[106:107], v[106:107], v[184:185], v[112:113] op_sel_hi:[1,0,1] neg_lo:[0,0,1] neg_hi:[0,0,1]
	v_pk_fma_f32 v[100:101], v[100:101], v[186:187], v[150:151] op_sel_hi:[1,0,1] neg_lo:[0,0,1] neg_hi:[0,0,1]
	v_pk_fma_f32 v[102:103], v[102:103], v[186:187], v[148:149] op_sel_hi:[1,0,1] neg_lo:[0,0,1] neg_hi:[0,0,1]
	v_pk_fma_f32 v[96:97], v[96:97], v[186:187], v[154:155] op_sel_hi:[1,0,1] neg_lo:[0,0,1] neg_hi:[0,0,1]
	v_pk_fma_f32 v[98:99], v[98:99], v[186:187], v[152:153] op_sel_hi:[1,0,1] neg_lo:[0,0,1] neg_hi:[0,0,1]
	v_exp_f32_e32 v176, v108
	v_exp_f32_e32 v177, v109
	v_exp_f32_e32 v178, v110
	v_exp_f32_e32 v179, v111
	v_exp_f32_e32 v180, v104
	v_exp_f32_e32 v181, v105
	v_exp_f32_e32 v182, v106
	v_exp_f32_e32 v183, v107
	v_pk_mul_f32 v[100:101], v[108:109], v[100:101]
	v_pk_mul_f32 v[102:103], v[110:111], v[102:103]
	v_pk_mul_f32 v[96:97], v[104:105], v[96:97]
	v_pk_mul_f32 v[98:99], v[106:107], v[98:99]
	v_pk_add_f32 v[176:177], v[176:177], s[100:101]
	v_pk_add_f32 v[178:179], v[178:179], s[100:101]
	v_pk_add_f32 v[180:181], v[180:181], s[100:101]
	v_pk_add_f32 v[182:183], v[182:183], s[100:101]
	v_rcp_f32_e32 v176, v176
	v_rcp_f32_e32 v177, v177
	v_rcp_f32_e32 v178, v178
	v_rcp_f32_e32 v179, v179
	v_rcp_f32_e32 v180, v180
	v_rcp_f32_e32 v181, v181
	v_rcp_f32_e32 v182, v182
	v_rcp_f32_e32 v183, v183
	v_add_u32_e32 v240, 0x16000, v239
	v_pk_mul_f32 v[100:101], v[100:101], v[176:177]
	v_pk_mul_f32 v[102:103], v[102:103], v[178:179]
	v_pk_mul_f32 v[96:97], v[96:97], v[180:181]
	v_pk_mul_f32 v[98:99], v[98:99], v[182:183]
	v_cvt_pk_bf16_f32 v188, v100, v101
	v_cvt_pk_bf16_f32 v189, v102, v103
	v_cvt_pk_bf16_f32 v190, v96, v97
	v_cvt_pk_bf16_f32 v191, v98, v99
	global_store_dwordx4 v240, v[188:191], s[16:17]
	v_mul_f32_e32 v184, 0xbfb8aa3b, v232
	v_mul_f32_e32 v186, 0xbf317218, v232
	v_pk_fma_f32 v[92:93], v[92:93], v[184:185], v[146:147] op_sel_hi:[1,0,1] neg_lo:[0,0,1] neg_hi:[0,0,1]
; __device__ __forceinline__ unsigned cvtpk(float lo, float hi) { f32x2_t v = {lo, hi}; bf16x2_t b = __builtin_convertvector(v, bf16x2_t); return __builtin_bit_cast(unsigned, b); }
; __device__ __forceinline__ float silu2(float g2, float u2) { return (g2 * u2) * __builtin_amdgcn_rcpf(1.0f + __builtin_amdgcn_exp2f(g2)); }
;     __device__ __forceinline__ void operator()(const f32x4 (&acc)[2][2][4][2], const Unit& u, int wr, int wc, int fr, int fq, int tid, const Pre& pre) const {
;     ...
;             for (int m = 0; m < 4; ++m) { bf16_t* rowp = O + (size_t)(row0 + ai * HALF + m * 16) * FF + col0;
;                 const float rs = scr[ai * HALF + wr * 64 + m * 16 + fr]; const float rsg = rs * (-LOG2E), rsu = rs * (-1.0f / LOG2E);
;                 const f32x4 g0 = acc[ai][0][m][0] * rsg + sg0, g1 = acc[ai][0][m][1] * rsg + sg1, u0 = acc[ai][1][m][0] * rsu + su0, u1 = acc[ai][1][m][1] * rsu + su1;
;                 u32x4 w; w.x = cvtpk(silu2(g0[0], u0[0]), silu2(g0[1], u0[1])); w.y = cvtpk(silu2(g0[2], u0[2]), silu2(g0[3], u0[3]));
;                 w.z = cvtpk(silu2(g1[0], u1[0]), silu2(g1[1], u1[1])); w.w = cvtpk(silu2(g1[2], u1[2]), silu2(g1[3], u1[3]));
;                 *(u32x4*)rowp = w; }
	v_pk_fma_f32 v[94:95], v[94:95], v[184:185], v[144:145] op_sel_hi:[1,0,1] neg_lo:[0,0,1] neg_hi:[0,0,1]
	v_pk_fma_f32 v[88:89], v[88:89], v[184:185], v[114:115] op_sel_hi:[1,0,1] neg_lo:[0,0,1] neg_hi:[0,0,1]
	v_pk_fma_f32 v[90:91], v[90:91], v[184:185], v[112:113] op_sel_hi:[1,0,1] neg_lo:[0,0,1] neg_hi:[0,0,1]
	v_pk_fma_f32 v[84:85], v[84:85], v[186:187], v[150:151] op_sel_hi:[1,0,1] neg_lo:[0,0,1] neg_hi:[0,0,1]
	v_pk_fma_f32 v[86:87], v[86:87], v[186:187], v[148:149] op_sel_hi:[1,0,1] neg_lo:[0,0,1] neg_hi:[0,0,1]
	v_pk_fma_f32 v[80:81], v[80:81], v[186:187], v[154:155] op_sel_hi:[1,0,1] neg_lo:[0,0,1] neg_hi:[0,0,1]
	v_pk_fma_f32 v[82:83], v[82:83], v[186:187], v[152:153] op_sel_hi:[1,0,1] neg_lo:[0,0,1] neg_hi:[0,0,1]
	v_exp_f32_e32 v176, v92
	v_exp_f32_e32 v177, v93
	v_exp_f32_e32 v178, v94
	v_exp_f32_e32 v179, v95
	v_exp_f32_e32 v180, v88
	v_exp_f32_e32 v181, v89
	v_exp_f32_e32 v182, v90
	v_exp_f32_e32 v183, v91
	v_pk_mul_f32 v[84:85], v[92:93], v[84:85]
	v_pk_mul_f32 v[86:87], v[94:95], v[86:87]
	v_pk_mul_f32 v[80:81], v[88:89], v[80:81]
	v_pk_mul_f32 v[82:83], v[90:91], v[82:83]
	v_pk_add_f32 v[176:177], v[176:177], s[100:101]
	v_pk_add_f32 v[178:179], v[178:179], s[100:101]
	v_pk_add_f32 v[180:181], v[180:181], s[100:101]
	v_pk_add_f32 v[182:183], v[182:183], s[100:101]
	v_rcp_f32_e32 v176, v176
	v_rcp_f32_e32 v177, v177
	v_rcp_f32_e32 v178, v178
	v_rcp_f32_e32 v179, v179
	v_rcp_f32_e32 v180, v180
	v_rcp_f32_e32 v181, v181
	v_rcp_f32_e32 v182, v182
	v_rcp_f32_e32 v183, v183
	v_add_u32_e32 v240, 0x2c000, v239
	v_pk_mul_f32 v[84:85], v[84:85], v[176:177]
	v_pk_mul_f32 v[86:87], v[86:87], v[178:179]
	v_pk_mul_f32 v[80:81], v[80:81], v[180:181]
	v_pk_mul_f32 v[82:83], v[82:83], v[182:183]
	v_cvt_pk_bf16_f32 v188, v84, v85
	v_cvt_pk_bf16_f32 v189, v86, v87
	v_cvt_pk_bf16_f32 v190, v80, v81
	v_cvt_pk_bf16_f32 v191, v82, v83
	global_store_dwordx4 v240, v[188:191], s[16:17]
	v_mul_f32_e32 v184, 0xbfb8aa3b, v233
	v_mul_f32_e32 v186, 0xbf317218, v233
	v_pk_fma_f32 v[76:77], v[76:77], v[184:185], v[146:147] op_sel_hi:[1,0,1] neg_lo:[0,0,1] neg_hi:[0,0,1]
	v_pk_fma_f32 v[78:79], v[78:79], v[184:185], v[144:145] op_sel_hi:[1,0,1] neg_lo:[0,0,1] neg_hi:[0,0,1]
	v_pk_fma_f32 v[72:73], v[72:73], v[184:185], v[114:115] op_sel_hi:[1,0,1] neg_lo:[0,0,1] neg_hi:[0,0,1]
	v_pk_fma_f32 v[74:75], v[74:75], v[184:185], v[112:113] op_sel_hi:[1,0,1] neg_lo:[0,0,1] neg_hi:[0,0,1]
	v_pk_fma_f32 v[68:69], v[68:69], v[186:187], v[150:151] op_sel_hi:[1,0,1] neg_lo:[0,0,1] neg_hi:[0,0,1]
	v_pk_fma_f32 v[70:71], v[70:71], v[186:187], v[148:149] op_sel_hi:[1,0,1] neg_lo:[0,0,1] neg_hi:[0,0,1]
	v_pk_fma_f32 v[64:65], v[64:65], v[186:187], v[154:155] op_sel_hi:[1,0,1] neg_lo:[0,0,1] neg_hi:[0,0,1]
	v_pk_fma_f32 v[66:67], v[66:67], v[186:187], v[152:153] op_sel_hi:[1,0,1] neg_lo:[0,0,1] neg_hi:[0,0,1]
	v_exp_f32_e32 v176, v76
	v_exp_f32_e32 v177, v77
	v_exp_f32_e32 v178, v78
	v_exp_f32_e32 v179, v79
	v_exp_f32_e32 v180, v72
	v_exp_f32_e32 v181, v73
	v_exp_f32_e32 v182, v74
	v_exp_f32_e32 v183, v75
	v_pk_mul_f32 v[68:69], v[76:77], v[68:69]
	v_pk_mul_f32 v[70:71], v[78:79], v[70:71]
	v_pk_mul_f32 v[64:65], v[72:73], v[64:65]
	v_pk_mul_f32 v[66:67], v[74:75], v[66:67]
	v_pk_add_f32 v[176:177], v[176:177], s[100:101]
	v_pk_add_f32 v[178:179], v[178:179], s[100:101]
	v_pk_add_f32 v[180:181], v[180:181], s[100:101]
	v_pk_add_f32 v[182:183], v[182:183], s[100:101]
	v_rcp_f32_e32 v176, v176
	v_rcp_f32_e32 v177, v177
	v_rcp_f32_e32 v178, v178
	v_rcp_f32_e32 v179, v179
	v_rcp_f32_e32 v180, v180
	v_rcp_f32_e32 v181, v181
	v_rcp_f32_e32 v182, v182
	v_rcp_f32_e32 v183, v183
	v_add_u32_e32 v240, 0x42000, v239
	v_pk_mul_f32 v[68:69], v[68:69], v[176:177]
	v_pk_mul_f32 v[70:71], v[70:71], v[178:179]
	v_pk_mul_f32 v[64:65], v[64:65], v[180:181]
	v_pk_mul_f32 v[66:67], v[66:67], v[182:183]
	v_cvt_pk_bf16_f32 v188, v68, v69
	v_cvt_pk_bf16_f32 v189, v70, v71
	v_cvt_pk_bf16_f32 v190, v64, v65
	v_cvt_pk_bf16_f32 v191, v66, v67
	global_store_dwordx4 v240, v[188:191], s[16:17]
	v_mul_f32_e32 v184, 0xbfb8aa3b, v234
	v_mul_f32_e32 v186, 0xbf317218, v234
	v_pk_fma_f32 v[60:61], v[60:61], v[184:185], v[146:147] op_sel_hi:[1,0,1] neg_lo:[0,0,1] neg_hi:[0,0,1]
	v_pk_fma_f32 v[62:63], v[62:63], v[184:185], v[144:145] op_sel_hi:[1,0,1] neg_lo:[0,0,1] neg_hi:[0,0,1]
	v_pk_fma_f32 v[56:57], v[56:57], v[184:185], v[114:115] op_sel_hi:[1,0,1] neg_lo:[0,0,1] neg_hi:[0,0,1]
	v_pk_fma_f32 v[58:59], v[58:59], v[184:185], v[112:113] op_sel_hi:[1,0,1] neg_lo:[0,0,1] neg_hi:[0,0,1]
	v_pk_fma_f32 v[52:53], v[52:53], v[186:187], v[150:151] op_sel_hi:[1,0,1] neg_lo:[0,0,1] neg_hi:[0,0,1]
	v_pk_fma_f32 v[54:55], v[54:55], v[186:187], v[148:149] op_sel_hi:[1,0,1] neg_lo:[0,0,1] neg_hi:[0,0,1]
	v_pk_fma_f32 v[48:49], v[48:49], v[186:187], v[154:155] op_sel_hi:[1,0,1] neg_lo:[0,0,1] neg_hi:[0,0,1]
	v_pk_fma_f32 v[50:51], v[50:51], v[186:187], v[152:153] op_sel_hi:[1,0,1] neg_lo:[0,0,1] neg_hi:[0,0,1]
	v_exp_f32_e32 v176, v60
	v_exp_f32_e32 v177, v61
	v_exp_f32_e32 v178, v62
	v_exp_f32_e32 v179, v63
	v_exp_f32_e32 v180, v56
	v_exp_f32_e32 v181, v57
	v_exp_f32_e32 v182, v58
	v_exp_f32_e32 v183, v59
	v_pk_mul_f32 v[52:53], v[60:61], v[52:53]
	v_pk_mul_f32 v[54:55], v[62:63], v[54:55]
	v_pk_mul_f32 v[48:49], v[56:57], v[48:49]
	v_pk_mul_f32 v[50:51], v[58:59], v[50:51]
	v_pk_add_f32 v[176:177], v[176:177], s[100:101]
	v_pk_add_f32 v[178:179], v[178:179], s[100:101]
	v_pk_add_f32 v[180:181], v[180:181], s[100:101]
	v_pk_add_f32 v[182:183], v[182:183], s[100:101]
	v_rcp_f32_e32 v176, v176
	v_rcp_f32_e32 v177, v177
	v_rcp_f32_e32 v178, v178
	v_rcp_f32_e32 v179, v179
	v_rcp_f32_e32 v180, v180
	v_rcp_f32_e32 v181, v181
; __device__ __forceinline__ unsigned cvtpk(float lo, float hi) { f32x2_t v = {lo, hi}; bf16x2_t b = __builtin_convertvector(v, bf16x2_t); return __builtin_bit_cast(unsigned, b); }
; __device__ __forceinline__ float silu2(float g2, float u2) { return (g2 * u2) * __builtin_amdgcn_rcpf(1.0f + __builtin_amdgcn_exp2f(g2)); }
; #define PG8_BAR __builtin_amdgcn_s_barrier()
;     __device__ __forceinline__ void operator()(const f32x4 (&acc)[2][2][4][2], const Unit& u, int wr, int wc, int fr, int fq, int tid, const Pre& pre) const {
;     ...
;             for (int m = 0; m < 4; ++m) { bf16_t* rowp = O + (size_t)(row0 + ai * HALF + m * 16) * FF + col0;
;                 const float rs = scr[ai * HALF + wr * 64 + m * 16 + fr]; const float rsg = rs * (-LOG2E), rsu = rs * (-1.0f / LOG2E);
;                 const f32x4 g0 = acc[ai][0][m][0] * rsg + sg0, g1 = acc[ai][0][m][1] * rsg + sg1, u0 = acc[ai][1][m][0] * rsu + su0, u1 = acc[ai][1][m][1] * rsu + su1;
;                 u32x4 w; w.x = cvtpk(silu2(g0[0], u0[0]), silu2(g0[1], u0[1])); w.y = cvtpk(silu2(g0[2], u0[2]), silu2(g0[3], u0[3]));
;                 w.z = cvtpk(silu2(g1[0], u1[0]), silu2(g1[1], u1[1])); w.w = cvtpk(silu2(g1[2], u1[2]), silu2(g1[3], u1[3]));
;                 *(u32x4*)rowp = w; }
; template <class Epi, class Sched>
; __device__ __forceinline__ void gemm_phase(LAS unsigned char* lds, const Gemm g, const Sched& S, const Epi& E, const int tid) {
;     ...
;         if (!has_next) break;
; #pragma unroll
;         for (int a = 0; a < 2; ++a)
; #pragma unroll
;             for (int b = 0; b < 2; ++b)
; #pragma unroll
;                 for (int m = 0; m < 4; ++m)
; #pragma unroll
;                     for (int n = 0; n < 2; ++n) acc[a][b][m][n] = (f32x4){0.f, 0.f, 0.f, 0.f};
;         cur = nxt; cA = nA; cB = nB; ++ui;
;         if (wr == 1) PG8_BAR;
	v_rcp_f32_e32 v182, v182
	v_rcp_f32_e32 v183, v183
	v_add_u32_e32 v240, 0xb0000, v239
	v_pk_mul_f32 v[52:53], v[52:53], v[176:177]
	v_pk_mul_f32 v[54:55], v[54:55], v[178:179]
	v_pk_mul_f32 v[48:49], v[48:49], v[180:181]
	v_pk_mul_f32 v[50:51], v[50:51], v[182:183]
	v_cvt_pk_bf16_f32 v188, v52, v53
	v_cvt_pk_bf16_f32 v189, v54, v55
	v_cvt_pk_bf16_f32 v190, v48, v49
	v_cvt_pk_bf16_f32 v191, v50, v51
	global_store_dwordx4 v240, v[188:191], s[16:17]
	v_mul_f32_e32 v184, 0xbfb8aa3b, v236
	v_mul_f32_e32 v186, 0xbf317218, v236
	v_pk_fma_f32 v[44:45], v[44:45], v[184:185], v[146:147] op_sel_hi:[1,0,1] neg_lo:[0,0,1] neg_hi:[0,0,1]
	v_pk_fma_f32 v[46:47], v[46:47], v[184:185], v[144:145] op_sel_hi:[1,0,1] neg_lo:[0,0,1] neg_hi:[0,0,1]
	v_pk_fma_f32 v[40:41], v[40:41], v[184:185], v[114:115] op_sel_hi:[1,0,1] neg_lo:[0,0,1] neg_hi:[0,0,1]
	v_pk_fma_f32 v[42:43], v[42:43], v[184:185], v[112:113] op_sel_hi:[1,0,1] neg_lo:[0,0,1] neg_hi:[0,0,1]
	v_pk_fma_f32 v[36:37], v[36:37], v[186:187], v[150:151] op_sel_hi:[1,0,1] neg_lo:[0,0,1] neg_hi:[0,0,1]
	v_pk_fma_f32 v[38:39], v[38:39], v[186:187], v[148:149] op_sel_hi:[1,0,1] neg_lo:[0,0,1] neg_hi:[0,0,1]
	v_pk_fma_f32 v[32:33], v[32:33], v[186:187], v[154:155] op_sel_hi:[1,0,1] neg_lo:[0,0,1] neg_hi:[0,0,1]
	v_pk_fma_f32 v[34:35], v[34:35], v[186:187], v[152:153] op_sel_hi:[1,0,1] neg_lo:[0,0,1] neg_hi:[0,0,1]
	v_exp_f32_e32 v176, v44
	v_exp_f32_e32 v177, v45
	v_exp_f32_e32 v178, v46
	v_exp_f32_e32 v179, v47
	v_exp_f32_e32 v180, v40
	v_exp_f32_e32 v181, v41
	v_exp_f32_e32 v182, v42
	v_exp_f32_e32 v183, v43
	v_pk_mul_f32 v[36:37], v[44:45], v[36:37]
	v_pk_mul_f32 v[38:39], v[46:47], v[38:39]
	v_pk_mul_f32 v[32:33], v[40:41], v[32:33]
	v_pk_mul_f32 v[34:35], v[42:43], v[34:35]
	v_pk_add_f32 v[176:177], v[176:177], s[100:101]
	v_pk_add_f32 v[178:179], v[178:179], s[100:101]
	v_pk_add_f32 v[180:181], v[180:181], s[100:101]
	v_pk_add_f32 v[182:183], v[182:183], s[100:101]
	v_rcp_f32_e32 v176, v176
	v_rcp_f32_e32 v177, v177
	v_rcp_f32_e32 v178, v178
	v_rcp_f32_e32 v179, v179
	v_rcp_f32_e32 v180, v180
	v_rcp_f32_e32 v181, v181
	v_rcp_f32_e32 v182, v182
	v_rcp_f32_e32 v183, v183
	v_add_u32_e32 v240, 0xc6000, v239
	v_pk_mul_f32 v[36:37], v[36:37], v[176:177]
	v_pk_mul_f32 v[38:39], v[38:39], v[178:179]
	v_pk_mul_f32 v[32:33], v[32:33], v[180:181]
	v_pk_mul_f32 v[34:35], v[34:35], v[182:183]
	v_cvt_pk_bf16_f32 v188, v36, v37
	v_cvt_pk_bf16_f32 v189, v38, v39
	v_cvt_pk_bf16_f32 v190, v32, v33
	v_cvt_pk_bf16_f32 v191, v34, v35
	global_store_dwordx4 v240, v[188:191], s[16:17]
	v_mul_f32_e32 v184, 0xbfb8aa3b, v237
	v_mul_f32_e32 v186, 0xbf317218, v237
	v_pk_fma_f32 v[28:29], v[28:29], v[184:185], v[146:147] op_sel_hi:[1,0,1] neg_lo:[0,0,1] neg_hi:[0,0,1]
	v_pk_fma_f32 v[30:31], v[30:31], v[184:185], v[144:145] op_sel_hi:[1,0,1] neg_lo:[0,0,1] neg_hi:[0,0,1]
	v_pk_fma_f32 v[24:25], v[24:25], v[184:185], v[114:115] op_sel_hi:[1,0,1] neg_lo:[0,0,1] neg_hi:[0,0,1]
	v_pk_fma_f32 v[26:27], v[26:27], v[184:185], v[112:113] op_sel_hi:[1,0,1] neg_lo:[0,0,1] neg_hi:[0,0,1]
	v_pk_fma_f32 v[20:21], v[20:21], v[186:187], v[150:151] op_sel_hi:[1,0,1] neg_lo:[0,0,1] neg_hi:[0,0,1]
	v_pk_fma_f32 v[22:23], v[22:23], v[186:187], v[148:149] op_sel_hi:[1,0,1] neg_lo:[0,0,1] neg_hi:[0,0,1]
	v_pk_fma_f32 v[16:17], v[16:17], v[186:187], v[154:155] op_sel_hi:[1,0,1] neg_lo:[0,0,1] neg_hi:[0,0,1]
	v_pk_fma_f32 v[18:19], v[18:19], v[186:187], v[152:153] op_sel_hi:[1,0,1] neg_lo:[0,0,1] neg_hi:[0,0,1]
	v_exp_f32_e32 v176, v28
	v_exp_f32_e32 v177, v29
	v_exp_f32_e32 v178, v30
	v_exp_f32_e32 v179, v31
	v_exp_f32_e32 v180, v24
	v_exp_f32_e32 v181, v25
	v_exp_f32_e32 v182, v26
	v_exp_f32_e32 v183, v27
	v_pk_mul_f32 v[20:21], v[28:29], v[20:21]
	v_pk_mul_f32 v[22:23], v[30:31], v[22:23]
	v_pk_mul_f32 v[16:17], v[24:25], v[16:17]
	v_pk_mul_f32 v[18:19], v[26:27], v[18:19]
	v_pk_add_f32 v[176:177], v[176:177], s[100:101]
	v_pk_add_f32 v[178:179], v[178:179], s[100:101]
	v_pk_add_f32 v[180:181], v[180:181], s[100:101]
	v_pk_add_f32 v[182:183], v[182:183], s[100:101]
	v_rcp_f32_e32 v176, v176
	v_rcp_f32_e32 v177, v177
	v_rcp_f32_e32 v178, v178
	v_rcp_f32_e32 v179, v179
	v_rcp_f32_e32 v180, v180
	v_rcp_f32_e32 v181, v181
	v_rcp_f32_e32 v182, v182
	v_rcp_f32_e32 v183, v183
	v_add_u32_e32 v240, 0xdc000, v239
	v_pk_mul_f32 v[20:21], v[20:21], v[176:177]
	v_pk_mul_f32 v[22:23], v[22:23], v[178:179]
	v_pk_mul_f32 v[16:17], v[16:17], v[180:181]
	v_pk_mul_f32 v[18:19], v[18:19], v[182:183]
	v_cvt_pk_bf16_f32 v188, v20, v21
	v_cvt_pk_bf16_f32 v189, v22, v23
	v_cvt_pk_bf16_f32 v190, v16, v17
	v_cvt_pk_bf16_f32 v191, v18, v19
	global_store_dwordx4 v240, v[188:191], s[16:17]
	v_mul_f32_e32 v184, 0xbfb8aa3b, v238
	v_mul_f32_e32 v186, 0xbf317218, v238
	v_pk_fma_f32 v[12:13], v[12:13], v[184:185], v[146:147] op_sel_hi:[1,0,1] neg_lo:[0,0,1] neg_hi:[0,0,1]
	v_pk_fma_f32 v[14:15], v[14:15], v[184:185], v[144:145] op_sel_hi:[1,0,1] neg_lo:[0,0,1] neg_hi:[0,0,1]
	v_pk_fma_f32 v[8:9], v[8:9], v[184:185], v[114:115] op_sel_hi:[1,0,1] neg_lo:[0,0,1] neg_hi:[0,0,1]
	v_pk_fma_f32 v[10:11], v[10:11], v[184:185], v[112:113] op_sel_hi:[1,0,1] neg_lo:[0,0,1] neg_hi:[0,0,1]
	v_pk_fma_f32 v[4:5], v[4:5], v[186:187], v[150:151] op_sel_hi:[1,0,1] neg_lo:[0,0,1] neg_hi:[0,0,1]
	v_pk_fma_f32 v[6:7], v[6:7], v[186:187], v[148:149] op_sel_hi:[1,0,1] neg_lo:[0,0,1] neg_hi:[0,0,1]
	v_pk_fma_f32 v[0:1], v[0:1], v[186:187], v[154:155] op_sel_hi:[1,0,1] neg_lo:[0,0,1] neg_hi:[0,0,1]
	v_pk_fma_f32 v[2:3], v[2:3], v[186:187], v[152:153] op_sel_hi:[1,0,1] neg_lo:[0,0,1] neg_hi:[0,0,1]
	v_exp_f32_e32 v176, v12
	v_exp_f32_e32 v177, v13
	v_exp_f32_e32 v178, v14
	v_exp_f32_e32 v179, v15
	v_exp_f32_e32 v180, v8
	v_exp_f32_e32 v181, v9
	v_exp_f32_e32 v182, v10
	v_exp_f32_e32 v183, v11
	v_pk_mul_f32 v[4:5], v[12:13], v[4:5]
	v_pk_mul_f32 v[6:7], v[14:15], v[6:7]
	v_pk_mul_f32 v[0:1], v[8:9], v[0:1]
	v_pk_mul_f32 v[2:3], v[10:11], v[2:3]
	v_pk_add_f32 v[176:177], v[176:177], s[100:101]
	v_pk_add_f32 v[178:179], v[178:179], s[100:101]
	v_pk_add_f32 v[180:181], v[180:181], s[100:101]
	v_pk_add_f32 v[182:183], v[182:183], s[100:101]
	v_rcp_f32_e32 v176, v176
	v_rcp_f32_e32 v177, v177
	v_rcp_f32_e32 v178, v178
	v_rcp_f32_e32 v179, v179
	v_rcp_f32_e32 v180, v180
	v_rcp_f32_e32 v181, v181
	v_rcp_f32_e32 v182, v182
	v_rcp_f32_e32 v183, v183
	v_add_u32_e32 v240, 0xf2000, v239
	v_pk_mul_f32 v[4:5], v[4:5], v[176:177]
	v_pk_mul_f32 v[6:7], v[6:7], v[178:179]
	v_pk_mul_f32 v[0:1], v[0:1], v[180:181]
	v_pk_mul_f32 v[2:3], v[2:3], v[182:183]
	v_cvt_pk_bf16_f32 v188, v4, v5
	v_cvt_pk_bf16_f32 v189, v6, v7
	v_cvt_pk_bf16_f32 v190, v0, v1
	v_cvt_pk_bf16_f32 v191, v2, v3
	global_store_dwordx4 v240, v[188:191], s[16:17]
	s_mov_b64 s[64:65], -1
	s_andn2_b64 vcc, exec, s[6:7]
	s_cbranch_vccnz .LBB0_162
	s_andn2_b64 vcc, exec, s[0:1]
	s_cbranch_vccnz .LBB0_161
	s_barrier
	s_branch .LBB0_161
